# SWA head loop: next head's q fragment and sink prefetched into v176-v192 during the current head (head 0 loads its own), counted waits (on top of v54)
# speedup vs baseline: 1.0031x; 1.0030x over previous
; #define LAS __attribute__((address_space(3)))
; DI void load_q(bf16x8 (&qf)[4], const bf16_t* qrow, int h) {
; #pragma unroll
;     for (int s = 0; s < 4; ++s) qf[s] = *(const bf16x8*)(qrow + 16 * s + 8 * h);
; }
; DI void swa_wg_unit(bf16_t* act, int b, int hk, int Qb, const float* sinks_l, LAS const float* tabS, LAS unsigned char* lds, int wid, int lane) {
;     ...
;     for (int g = 0; g < 4; ++g) {
;         const int hq = 4 * hk + g;
;         LAS const float* tab = tabS + hq * 128;
;         bf16x8 qf[4]; load_q(qf, act + rowq * PITCH + C_QC + hq * 64, h);
;         f32x16 o0, o1;
; #pragma unroll
;         for (int i = 0; i < 16; ++i) { o0[i] = 0.f; o1[i] = 0.f; }
;         float m = sinks_l[hq] * LOG2E, l = (h == 0) ? 1.0f : 0.f;
;         for (int t = tlo; t <= (q0 >> 6); ++t) {
.LBB0_378:
	s_add_i32 s10, s13, s14
	s_lshl_b32 s38, s10, 7
	v_lshl_add_u64 v[104:105], v[102:103], 0, s[38:39]
	v_mov_b32_e32 v31, 0
	s_andn2_b64 vcc, exec, s[8:9]
	v_mov_b32_e32 v30, 0
	v_mov_b32_e32 v29, 0
	v_mov_b32_e32 v28, 0
	v_mov_b32_e32 v27, 0
	v_mov_b32_e32 v26, 0
	v_mov_b32_e32 v25, 0
	v_mov_b32_e32 v24, 0
	v_mov_b32_e32 v23, 0
	v_mov_b32_e32 v22, 0
	v_mov_b32_e32 v21, 0
	v_mov_b32_e32 v20, 0
	v_mov_b32_e32 v19, 0
	v_mov_b32_e32 v18, 0
	v_mov_b32_e32 v17, 0
	v_mov_b32_e32 v16, 0
	v_mov_b32_e32 v47, 0
	v_mov_b32_e32 v46, 0
	v_mov_b32_e32 v45, 0
	v_mov_b32_e32 v44, 0
	v_mov_b32_e32 v43, 0
	v_mov_b32_e32 v42, 0
	v_mov_b32_e32 v41, 0
	v_mov_b32_e32 v40, 0
	v_mov_b32_e32 v39, 0
	v_mov_b32_e32 v38, 0
	v_mov_b32_e32 v37, 0
	v_mov_b32_e32 v36, 0
	v_mov_b32_e32 v35, 0
	v_mov_b32_e32 v34, 0
	v_mov_b32_e32 v33, 0
	v_mov_b32_e32 v32, 0
	v_lshl_add_u64 v[142:143], v[100:101], 0, s[38:39]
	global_load_dwordx2 v[160:161], v[142:143], off
	global_load_dwordx2 v[162:163], v[142:143], off offset:16
	global_load_dwordx2 v[164:165], v[142:143], off offset:32
	global_load_dwordx2 v[166:167], v[142:143], off offset:48
	global_load_dwordx2 v[168:169], v[142:143], off offset:64
	global_load_dwordx2 v[170:171], v[142:143], off offset:80
	global_load_dwordx2 v[172:173], v[142:143], off offset:96
	global_load_dwordx2 v[174:175], v[142:143], off offset:112
	v_mov_b32_e32 v118, v108
	s_cbranch_vccnz .LBB0_377
	s_lshl_b32 s11, s10, 9
	s_add_i32 s24, s11, 0
	s_mov_b32 s11, s39
	s_add_i32 s24, s24, 0x21080
	s_lshl_b64 s[26:27], s[10:11], 2
	s_add_u32 s26, s16, s26
	s_addc_u32 s27, s17, s27
	s_cmp_eq_u32 s13, 0
	s_cbranch_scc0 .Lswq_mov
	global_load_dwordx4 v[80:83], v[104:105], off
	global_load_dwordx4 v[84:87], v[104:105], off offset:32
	global_load_dword v32, v1, s[26:27]
	global_load_dwordx4 v[88:91], v[104:105], off offset:64
	global_load_dwordx4 v[92:95], v[104:105], off offset:96
	s_branch .Lswq_pf
.Lswq_mov:
	v_mov_b32_e32 v80, v176
	v_mov_b32_e32 v81, v177
	v_mov_b32_e32 v82, v178
	v_mov_b32_e32 v83, v179
	v_mov_b32_e32 v84, v180
	v_mov_b32_e32 v85, v181
	v_mov_b32_e32 v86, v182
	v_mov_b32_e32 v87, v183
	v_mov_b32_e32 v88, v184
	v_mov_b32_e32 v89, v185
	v_mov_b32_e32 v90, v186
	v_mov_b32_e32 v91, v187
	v_mov_b32_e32 v92, v188
	v_mov_b32_e32 v93, v189
	v_mov_b32_e32 v94, v190
	v_mov_b32_e32 v95, v191
	v_mov_b32_e32 v32, v192
.Lswq_pf:
	s_add_i32 s98, s13, 1
	s_min_i32 s98, s98, 3
	s_add_i32 s98, s98, s14
	s_lshl_b32 s100, s98, 7
	s_mov_b32 s101, 0
	v_lshl_add_u64 v[142:143], v[102:103], 0, s[100:101]
	s_lshl_b32 s100, s98, 2
	s_add_u32 s100, s16, s100
	s_addc_u32 s101, s17, 0
	global_load_dwordx4 v[176:179], v[142:143], off
	global_load_dwordx4 v[180:183], v[142:143], off offset:32
	global_load_dword v192, v1, s[100:101]
	global_load_dwordx4 v[184:187], v[142:143], off offset:64
	global_load_dwordx4 v[188:191], v[142:143], off offset:96
	v_mov_b32_e32 v14, v1
	v_mov_b32_e32 v15, v1
	v_mov_b32_e32 v0, v1
	v_mov_b32_e32 v2, v1
	v_mov_b32_e32 v3, v1
	v_mov_b32_e32 v4, v1
	v_mov_b32_e32 v5, v1
	v_mov_b32_e32 v6, v1
	v_mov_b32_e32 v7, v1
	v_mov_b32_e32 v8, v1
	v_mov_b32_e32 v9, v1
	v_mov_b32_e32 v10, v1
	v_mov_b32_e32 v11, v1
	v_mov_b32_e32 v12, v1
	v_mov_b32_e32 v13, v1
	v_mov_b64_e32 v[30:31], v[14:15]
	v_mov_b32_e32 v119, v117
	v_mov_b32_e32 v120, v99
	s_mov_b32 s11, s23
	v_mov_b32_e32 v121, v97
	v_mov_b32_e32 v118, v108
	v_mov_b64_e32 v[28:29], v[12:13]
	v_mov_b64_e32 v[26:27], v[10:11]
	v_mov_b64_e32 v[24:25], v[8:9]
	v_mov_b64_e32 v[22:23], v[6:7]
	v_mov_b64_e32 v[20:21], v[4:5]
	v_mov_b64_e32 v[18:19], v[2:3]
	v_mov_b64_e32 v[16:17], v[0:1]
	s_waitcnt vmcnt(7)
	v_mul_f32_e32 v122, 0x3fb8aa3b, v32
	v_mov_b64_e32 v[46:47], v[14:15]
	v_mov_b64_e32 v[44:45], v[12:13]
	v_mov_b64_e32 v[42:43], v[10:11]
	v_mov_b64_e32 v[40:41], v[8:9]
	v_mov_b64_e32 v[38:39], v[6:7]
	v_mov_b64_e32 v[36:37], v[4:5]
	v_mov_b64_e32 v[34:35], v[2:3]
	v_mov_b64_e32 v[32:33], v[0:1]
	s_branch .LBB0_381

; #define LAS __attribute__((address_space(3)))
; DI void swa_wg_unit(bf16_t* act, int b, int hk, int Qb, const float* sinks_l, LAS const float* tabS, LAS unsigned char* lds, int wid, int lane) {
;     ...
;         for (int t = tlo; t <= (q0 >> 6); ++t) {
;             const int kv0 = t * 64;
;             LAS const unsigned char* Ks = lds + (t_hi - t) * 16384; LAS const unsigned char* Vs = Ks + 8192;
;             f32x16 p0, p1;
; #pragma unroll
;             for (int i = 0; i < 16; ++i) { p0[i] = 0.f; p1[i] = 0.f; }
;             qk_tile(p0, p1, Ks, qf, r, h);
;             const int dq = qpos - kv0 - 4 * h;
;             float tmax = NEG_INF;
; #pragma unroll
;             for (int half = 0; half < 2; ++half) {
;                 float tb[16];
; #pragma unroll
;                 for (int i = 0; i < 16; ++i) { const int d = dq - 32 * half - ((i & 3) + 8 * (i >> 2)); tb[i] = tab[d < 0 ? 0 : (d > 127 ? 127 : d)]; }
; #pragma unroll
;                 for (int i = 0; i < 16; ++i) asm volatile("" : "+v"(tb[i]));
; #pragma unroll
;                 for (int i = 0; i < 16; ++i) { const int d = dq - 32 * half - ((i & 3) + 8 * (i >> 2)); const bool valid = (unsigned)d < 128u;
;                     if (half == 0) { p0[i] = valid ? p0[i] + tb[i] : NEG_INF; tmax = fmaxf(tmax, p0[i]); } else { p1[i] = valid ? p1[i] + tb[i] : NEG_INF; tmax = fmaxf(tmax, p1[i]); } }
.LBB0_381:
	v_add_u32_e32 v0, s12, v119
	ds_read_b128 v[2:5], v0
	ds_read_b128 v[6:9], v0 offset:512
	v_add_u32_e32 v12, -10, v121
	v_add_u32_e32 v14, -11, v121
	v_add_u32_e32 v123, -16, v121
	s_waitcnt lgkmcnt(1)
	v_mfma_f32_32x32x16_bf16 v[64:79], v[2:5], v[80:83], 0
	v_subrev_u32_e32 v125, 17, v121
	v_subrev_u32_e32 v127, 18, v121
	v_subrev_u32_e32 v129, 19, v121
	v_subrev_u32_e32 v131, 24, v121
	v_subrev_u32_e32 v133, 25, v121
	v_subrev_u32_e32 v135, 26, v121
	v_subrev_u32_e32 v137, 27, v121
	s_waitcnt lgkmcnt(0)
	v_mfma_f32_32x32x16_bf16 v[48:63], v[6:9], v[80:83], 0
	ds_read_b128 v[2:5], v0 offset:2048
	ds_read_b128 v[6:9], v0 offset:2560
	v_add_u32_e32 v10, -8, v121
	v_add_u32_e32 v11, -9, v121
	v_med3_i32 v13, v12, 0, v236
	v_med3_i32 v15, v14, 0, v236
	v_med3_i32 v124, v123, 0, v236
	v_med3_i32 v126, v125, 0, v236
	s_waitcnt lgkmcnt(1)
	v_mfma_f32_32x32x16_bf16 v[64:79], v[2:5], v[84:87], v[64:79]
	v_med3_i32 v128, v127, 0, v236
	v_med3_i32 v130, v129, 0, v236
	v_med3_i32 v132, v131, 0, v236
	v_med3_i32 v134, v133, 0, v236
	v_med3_i32 v136, v135, 0, v236
	v_med3_i32 v138, v137, 0, v236
	v_lshl_add_u32 v13, v13, 2, s24
	s_waitcnt lgkmcnt(0)
	v_mfma_f32_32x32x16_bf16 v[48:63], v[6:9], v[84:87], v[48:63]
	ds_read_b128 v[2:5], v0 offset:4096
	ds_read_b128 v[6:9], v0 offset:4608
	v_lshl_add_u32 v15, v15, 2, s24
	v_lshl_add_u32 v124, v124, 2, s24
	v_lshl_add_u32 v126, v126, 2, s24
	v_lshl_add_u32 v128, v128, 2, s24
	v_lshl_add_u32 v130, v130, 2, s24
	v_lshl_add_u32 v132, v132, 2, s24
	s_waitcnt vmcnt(6) lgkmcnt(1)
	v_mfma_f32_32x32x16_bf16 v[64:79], v[2:5], v[88:91], v[64:79]
	v_lshl_add_u32 v134, v134, 2, s24
	v_lshl_add_u32 v136, v136, 2, s24
	v_lshl_add_u32 v138, v138, 2, s24
	v_cmp_gt_u32_e32 vcc, s30, v121
	s_waitcnt lgkmcnt(0)
	v_mfma_f32_32x32x16_bf16 v[48:63], v[6:9], v[88:91], v[48:63]
	ds_read_b128 v[2:5], v0 offset:6144
	ds_read_b128 v[6:9], v0 offset:6656
	v_med3_i32 v0, v121, 0, v236
	v_lshl_add_u32 v0, v0, 2, s24
	s_waitcnt vmcnt(5) lgkmcnt(1)
	v_mfma_f32_32x32x16_bf16 v[64:79], v[2:5], v[92:95], v[64:79]
	v_add_u32_e32 v2, -1, v121
	v_add_u32_e32 v4, -2, v121
	v_med3_i32 v3, v2, 0, v236
	v_med3_i32 v5, v4, 0, v236
	v_lshl_add_u32 v3, v3, 2, s24
	v_lshl_add_u32 v5, v5, 2, s24
	s_waitcnt lgkmcnt(0)
	v_mfma_f32_32x32x16_bf16 v[48:63], v[6:9], v[92:95], v[48:63]
	v_add_u32_e32 v8, -3, v121
	v_med3_i32 v6, v8, 0, v236
	v_med3_i32 v7, v10, 0, v236
	v_med3_i32 v9, v11, 0, v236
	v_lshl_add_u32 v6, v6, 2, s24
	v_lshl_add_u32 v7, v7, 2, s24
	v_lshl_add_u32 v9, v9, 2, s24
	ds_read_b32 v0, v0
	ds_read_b32 v3, v3
	ds_read_b32 v5, v5
	ds_read_b32 v139, v6
	ds_read_b32 v140, v7
	ds_read_b32 v141, v9
	ds_read_b32 v13, v13
	ds_read_b32 v15, v15
	ds_read_b32 v124, v124
	ds_read_b32 v126, v126
	ds_read_b32 v128, v128
	ds_read_b32 v130, v130
	ds_read_b32 v132, v132
	ds_read_b32 v134, v134
	ds_read_b32 v136, v136
	ds_read_b32 v138, v138
	s_waitcnt lgkmcnt(14)
	s_waitcnt lgkmcnt(13)
	s_waitcnt lgkmcnt(12)
	s_waitcnt lgkmcnt(11)
	s_waitcnt lgkmcnt(10)
	v_add_f32_e32 v0, v64, v0
	v_cndmask_b32_e32 v0, v235, v0, vcc
	v_cmp_gt_u32_e32 vcc, s30, v2
	v_add_f32_e32 v2, v65, v3
	v_add_f32_e32 v3, v66, v5
	v_cndmask_b32_e32 v7, v235, v2, vcc
	v_cmp_gt_u32_e32 vcc, s30, v4
	s_waitcnt lgkmcnt(9)
	s_waitcnt lgkmcnt(8)
	s_waitcnt lgkmcnt(7)
	v_max3_f32 v2, v0, s35, v7
	s_waitcnt lgkmcnt(6)
	v_cndmask_b32_e32 v6, v235, v3, vcc
	v_cmp_gt_u32_e32 vcc, s30, v8
	v_add_f32_e32 v3, v67, v139
	s_waitcnt lgkmcnt(5)
	s_waitcnt lgkmcnt(4)
	s_waitcnt lgkmcnt(3)
	s_waitcnt lgkmcnt(2)
	v_cndmask_b32_e32 v9, v235, v3, vcc
	v_cmp_gt_u32_e32 vcc, s30, v10
	v_add_f32_e32 v3, v68, v140
	v_max3_f32 v2, v2, v6, v9
	v_cndmask_b32_e32 v8, v235, v3, vcc
	v_cmp_gt_u32_e32 vcc, s30, v11
	v_add_f32_e32 v3, v69, v141
	s_waitcnt lgkmcnt(1)
	s_waitcnt lgkmcnt(0)
; DI float fast_exp2(float x) { return __builtin_amdgcn_exp2f(x); }
; DI float xhalf_max(float m) { auto rr = __builtin_amdgcn_permlane32_swap(__float_as_uint(m), __float_as_uint(m), false, false); return fmaxf(__uint_as_float(rr[0]), __uint_as_float(rr[1])); }
; DI void swa_wg_unit(bf16_t* act, int b, int hk, int Qb, const float* sinks_l, LAS const float* tabS, LAS unsigned char* lds, int wid, int lane) {
;     ...
;             for (int half = 0; half < 2; ++half) {
;                 float tb[16];
; #pragma unroll
;                 for (int i = 0; i < 16; ++i) { const int d = dq - 32 * half - ((i & 3) + 8 * (i >> 2)); tb[i] = tab[d < 0 ? 0 : (d > 127 ? 127 : d)]; }
; #pragma unroll
;                 for (int i = 0; i < 16; ++i) asm volatile("" : "+v"(tb[i]));
; #pragma unroll
;                 for (int i = 0; i < 16; ++i) { const int d = dq - 32 * half - ((i & 3) + 8 * (i >> 2)); const bool valid = (unsigned)d < 128u;
;                     if (half == 0) { p0[i] = valid ? p0[i] + tb[i] : NEG_INF; tmax = fmaxf(tmax, p0[i]); } else { p1[i] = valid ? p1[i] + tb[i] : NEG_INF; tmax = fmaxf(tmax, p1[i]); } }
;             }
;             tmax = xhalf_max(tmax);
;             const bool grow = (tmax - m) > 16.f;
;             if (__ballot(grow) != 0ull) {
;                 const float mn = grow ? tmax : m, alpha = fast_exp2(m - mn);
;                 l *= alpha; m = mn;
; #pragma unroll
;                 for (int i = 0; i < 16; ++i) { o0[i] *= alpha; o1[i] *= alpha; }
;             }
	v_subrev_u32_e32 v68, 33, v121
	v_cndmask_b32_e32 v11, v235, v3, vcc
	v_cmp_gt_u32_e32 vcc, s30, v12
	v_add_f32_e32 v3, v70, v13
	v_max3_f32 v2, v2, v8, v11
	v_cndmask_b32_e32 v10, v235, v3, vcc
	v_cmp_gt_u32_e32 vcc, s30, v14
	v_add_f32_e32 v3, v71, v15
	v_add_f32_e32 v5, v79, v138
	v_cndmask_b32_e32 v13, v235, v3, vcc
	v_cmp_gt_u32_e32 vcc, s30, v123
	v_add_f32_e32 v3, v72, v124
	v_max3_f32 v2, v2, v10, v13
	v_cndmask_b32_e32 v12, v235, v3, vcc
	v_cmp_gt_u32_e32 vcc, s30, v125
	v_add_f32_e32 v3, v73, v126
	v_subrev_u32_e32 v70, 34, v121
	v_cndmask_b32_e32 v14, v235, v3, vcc
	v_cmp_gt_u32_e32 vcc, s30, v127
	v_add_f32_e32 v3, v74, v128
	v_max3_f32 v2, v2, v12, v14
	v_cndmask_b32_e32 v15, v235, v3, vcc
	v_cmp_gt_u32_e32 vcc, s30, v129
	v_add_f32_e32 v3, v75, v130
	v_subrev_u32_e32 v72, 35, v121
	v_cndmask_b32_e32 v64, v235, v3, vcc
	v_max3_f32 v4, v2, v15, v64
	v_cmp_gt_u32_e32 vcc, s30, v131
	v_add_f32_e32 v2, v76, v132
	v_add_f32_e32 v3, v77, v134
	v_cndmask_b32_e32 v2, v235, v2, vcc
	v_cmp_gt_u32_e32 vcc, s30, v133
	v_subrev_u32_e32 v74, 40, v121
	v_subrev_u32_e32 v76, 41, v121
	v_cndmask_b32_e32 v3, v235, v3, vcc
	v_max3_f32 v65, v4, v2, v3
	v_cmp_gt_u32_e32 vcc, s30, v135
	v_add_f32_e32 v4, v78, v136
	v_subrev_u32_e32 v78, 42, v121
	v_cndmask_b32_e32 v4, v235, v4, vcc
	v_cmp_gt_u32_e32 vcc, s30, v137
	v_subrev_u32_e32 v123, 43, v121
	v_subrev_u32_e32 v125, 48, v121
	v_cndmask_b32_e32 v5, v235, v5, vcc
	v_max3_f32 v66, v65, v4, v5
	v_subrev_u32_e32 v65, 32, v121
	v_subrev_u32_e32 v127, 49, v121
	v_subrev_u32_e32 v129, 50, v121
	v_subrev_u32_e32 v131, 51, v121
	v_subrev_u32_e32 v133, 56, v121
	v_subrev_u32_e32 v135, 57, v121
	v_subrev_u32_e32 v137, 58, v121
	v_subrev_u32_e32 v139, 59, v121
	v_med3_i32 v67, v65, 0, v236
	v_med3_i32 v69, v68, 0, v236
	v_med3_i32 v71, v70, 0, v236
	v_med3_i32 v73, v72, 0, v236
	v_med3_i32 v75, v74, 0, v236
	v_med3_i32 v77, v76, 0, v236
	v_med3_i32 v79, v78, 0, v236
	v_med3_i32 v124, v123, 0, v236
	v_med3_i32 v126, v125, 0, v236
	v_med3_i32 v128, v127, 0, v236
	v_med3_i32 v130, v129, 0, v236
	v_med3_i32 v132, v131, 0, v236
	v_med3_i32 v134, v133, 0, v236
	v_med3_i32 v136, v135, 0, v236
	v_med3_i32 v138, v137, 0, v236
	v_med3_i32 v140, v139, 0, v236
	v_lshl_add_u32 v67, v67, 2, s24
	v_lshl_add_u32 v69, v69, 2, s24
	v_lshl_add_u32 v71, v71, 2, s24
	v_lshl_add_u32 v73, v73, 2, s24
	v_lshl_add_u32 v75, v75, 2, s24
	v_lshl_add_u32 v77, v77, 2, s24
	v_lshl_add_u32 v79, v79, 2, s24
	v_lshl_add_u32 v124, v124, 2, s24
	v_lshl_add_u32 v126, v126, 2, s24
	v_lshl_add_u32 v128, v128, 2, s24
	v_lshl_add_u32 v130, v130, 2, s24
	v_lshl_add_u32 v132, v132, 2, s24
	v_lshl_add_u32 v134, v134, 2, s24
	v_lshl_add_u32 v136, v136, 2, s24
	v_lshl_add_u32 v138, v138, 2, s24
	v_lshl_add_u32 v140, v140, 2, s24
	ds_read_b32 v67, v67
	ds_read_b32 v69, v69
	ds_read_b32 v71, v71
	ds_read_b32 v73, v73
	ds_read_b32 v75, v75
	ds_read_b32 v77, v77
	ds_read_b32 v79, v79
	ds_read_b32 v124, v124
	ds_read_b32 v126, v126
	ds_read_b32 v128, v128
	ds_read_b32 v130, v130
	ds_read_b32 v132, v132
	ds_read_b32 v134, v134
	ds_read_b32 v136, v136
	ds_read_b32 v138, v138
	ds_read_b32 v140, v140
	s_waitcnt lgkmcnt(14)
	v_cmp_gt_u32_e32 vcc, s30, v65
	v_add_f32_e32 v48, v48, v67
	s_waitcnt lgkmcnt(13)
	s_waitcnt lgkmcnt(12)
	s_waitcnt lgkmcnt(11)
	v_cndmask_b32_e32 v65, v235, v48, vcc
	v_cmp_gt_u32_e32 vcc, s30, v68
	v_add_f32_e32 v48, v49, v69
	v_add_f32_e32 v49, v50, v71
	v_cndmask_b32_e32 v67, v235, v48, vcc
	v_cmp_gt_u32_e32 vcc, s30, v70
	v_max3_f32 v48, v66, v65, v67
	s_waitcnt lgkmcnt(10)
	s_waitcnt lgkmcnt(9)
	s_waitcnt lgkmcnt(8)
	s_waitcnt lgkmcnt(7)
	v_cndmask_b32_e32 v66, v235, v49, vcc
	v_cmp_gt_u32_e32 vcc, s30, v72
	v_add_f32_e32 v49, v51, v73
	s_waitcnt lgkmcnt(6)
	s_waitcnt lgkmcnt(5)
	s_waitcnt lgkmcnt(4)
	s_waitcnt lgkmcnt(3)
	v_cndmask_b32_e32 v68, v235, v49, vcc
	v_cmp_gt_u32_e32 vcc, s30, v74
	v_add_f32_e32 v49, v52, v75
	v_max3_f32 v48, v48, v66, v68
	v_cndmask_b32_e32 v52, v235, v49, vcc
	v_cmp_gt_u32_e32 vcc, s30, v76
	v_add_f32_e32 v49, v53, v77
	s_waitcnt lgkmcnt(2)
	s_waitcnt lgkmcnt(1)
	s_waitcnt lgkmcnt(0)
	v_cndmask_b32_e32 v69, v235, v49, vcc
	v_cmp_gt_u32_e32 vcc, s30, v78
	v_add_f32_e32 v49, v54, v79
	v_max3_f32 v48, v48, v52, v69
	v_cndmask_b32_e32 v53, v235, v49, vcc
	v_cmp_gt_u32_e32 vcc, s30, v123
	v_add_f32_e32 v49, v55, v124
	s_nop 0
	v_cndmask_b32_e32 v55, v235, v49, vcc
	v_cmp_gt_u32_e32 vcc, s30, v125
	v_add_f32_e32 v49, v56, v126
	v_max3_f32 v48, v48, v53, v55
	v_cndmask_b32_e32 v54, v235, v49, vcc
	v_cmp_gt_u32_e32 vcc, s30, v127
	v_add_f32_e32 v49, v57, v128
	s_nop 0
	v_cndmask_b32_e32 v56, v235, v49, vcc
	v_cmp_gt_u32_e32 vcc, s30, v129
	v_add_f32_e32 v49, v58, v130
	v_max3_f32 v48, v48, v54, v56
	v_cndmask_b32_e32 v57, v235, v49, vcc
	v_cmp_gt_u32_e32 vcc, s30, v131
	v_add_f32_e32 v49, v59, v132
	s_nop 0
	v_cndmask_b32_e32 v58, v235, v49, vcc
	v_cmp_gt_u32_e32 vcc, s30, v133
	v_add_f32_e32 v49, v60, v134
	v_max3_f32 v48, v48, v57, v58
	v_cndmask_b32_e32 v50, v235, v49, vcc
	v_cmp_gt_u32_e32 vcc, s30, v135
	v_add_f32_e32 v49, v61, v136
	s_nop 0
	v_cndmask_b32_e32 v51, v235, v49, vcc
	v_max3_f32 v59, v48, v50, v51
	v_cmp_gt_u32_e32 vcc, s30, v137
	v_add_f32_e32 v48, v62, v138
	v_add_f32_e32 v49, v63, v140
	v_cndmask_b32_e32 v48, v235, v48, vcc
	v_cmp_gt_u32_e32 vcc, s30, v139
	s_nop 1
	v_cndmask_b32_e32 v49, v235, v49, vcc
	v_max3_f32 v59, v59, v48, v49
	v_mov_b32_e32 v60, v59
	s_nop 1
	v_permlane32_swap_b32_e32 v59, v60
	v_max_f32_e32 v60, v60, v60
	v_max_f32_e32 v59, v59, v59
	v_max_f32_e32 v59, v59, v60
	v_sub_f32_e32 v60, v59, v122
	v_cmp_lt_f32_e32 vcc, s90, v60
	s_cbranch_vccz .LBB0_380
	s_nop 0
	v_cndmask_b32_e32 v59, v122, v59, vcc
	v_sub_f32_e32 v60, v122, v59
	v_exp_f32_e32 v60, v60
	v_mov_b32_e32 v122, v59
	v_pk_mul_f32 v[46:47], v[46:47], v[60:61] op_sel_hi:[1,0]
	v_pk_mul_f32 v[44:45], v[44:45], v[60:61] op_sel_hi:[1,0]
	v_pk_mul_f32 v[42:43], v[42:43], v[60:61] op_sel_hi:[1,0]
	v_pk_mul_f32 v[40:41], v[40:41], v[60:61] op_sel_hi:[1,0]
	v_pk_mul_f32 v[38:39], v[38:39], v[60:61] op_sel_hi:[1,0]
	v_pk_mul_f32 v[36:37], v[36:37], v[60:61] op_sel_hi:[1,0]
	v_pk_mul_f32 v[34:35], v[34:35], v[60:61] op_sel_hi:[1,0]
	v_pk_mul_f32 v[32:33], v[32:33], v[60:61] op_sel_hi:[1,0]
	v_pk_mul_f32 v[30:31], v[30:31], v[60:61] op_sel_hi:[1,0]
	v_pk_mul_f32 v[28:29], v[28:29], v[60:61] op_sel_hi:[1,0]
	v_pk_mul_f32 v[26:27], v[26:27], v[60:61] op_sel_hi:[1,0]
	v_pk_mul_f32 v[24:25], v[24:25], v[60:61] op_sel_hi:[1,0]
	v_pk_mul_f32 v[22:23], v[22:23], v[60:61] op_sel_hi:[1,0]
	v_pk_mul_f32 v[20:21], v[20:21], v[60:61] op_sel_hi:[1,0]
	v_pk_mul_f32 v[18:19], v[18:19], v[60:61] op_sel_hi:[1,0]
	v_pk_mul_f32 v[16:17], v[16:17], v[60:61] op_sel_hi:[1,0]
	v_mul_f32_e32 v118, v118, v60
	s_branch .LBB0_380
